# NA tile loop: per-element mask/bias blocks straight-lined (v_add + v_cndmask), one uniform branch for context tiles
# baseline (speedup 1.0000x reference)
.LBB0_1557:
	s_or_b64 exec, exec, s[6:7]
	v_add_u32_e32 v207, s14, v122
	ds_read_b32 v208, v207 offset:37792
	ds_read_b32 v209, v207 offset:37800
	ds_read_b32 v210, v207 offset:37796
	ds_read_b32 v211, v207 offset:37804
	ds_read_b32 v212, v207 offset:37856
	ds_read_b32 v213, v207 offset:37864
	ds_read_b32 v214, v207 offset:37860
	ds_read_b32 v215, v207 offset:37868
	ds_read_b32 v216, v207 offset:37920
	ds_read_b32 v217, v207 offset:37928
	ds_read_b32 v218, v207 offset:37924
	ds_read_b32 v219, v207 offset:37932
	ds_read_b32 v220, v207 offset:37984
	ds_read_b32 v221, v207 offset:37992
	ds_read_b32 v222, v207 offset:37988
	ds_read_b32 v223, v207 offset:37996
	ds_read_b32 v224, v207 offset:37668
	ds_read_b32 v225, v207 offset:37676
	ds_read_b32 v226, v207 offset:37732
	ds_read_b32 v227, v207 offset:37740
	ds_read_b32 v228, v207 offset:37672
	ds_read_b32 v229, v207 offset:37680
	ds_read_b32 v230, v207 offset:37736
	ds_read_b32 v231, v207 offset:37744
	ds_read_b32 v232, v207 offset:37808
	ds_read_b32 v233, v207 offset:37872
	s_add_i32 s6, s15, -9
	v_mov_b32_e32 v133, s6
	v_cndmask_b32_e32 v133, v127, v133, vcc
	v_cmp_gt_u32_e64 s[58:59], 64, v133
	v_cmp_ge_i32_e64 s[60:61], v127, v117
	s_and_b64 s[96:97], s[58:59], s[66:67]
	v_cmp_lt_i32_e64 s[56:57], v127, v118
	s_and_b64 s[6:7], s[96:97], s[60:61]
	v_cndmask_b32_e64 v133, 0, 1, s[4:5]
	v_cmp_ne_u32_e64 s[54:55], 1, v133
	s_and_b64 s[4:5], s[6:7], s[56:57]
	s_and_b64 vcc, exec, s[54:55]
	s_cbranch_vccz .Lnaa_loc
	v_readlane_b32 s4, v254, 63
	v_readlane_b32 s5, v255, 0
	s_and_b64 s[62:63], s[58:59], s[4:5]
	s_and_b64 s[4:5], s[62:63], s[60:61]
	s_and_b64 s[4:5], s[4:5], s[56:57]
	s_and_b64 s[4:5], s[58:59], s[2:3]
	s_and_b64 s[6:7], s[4:5], s[60:61]
	s_and_b64 s[6:7], s[6:7], s[56:57]
	s_and_b64 s[6:7], s[58:59], s[68:69]
	s_and_b64 s[16:17], s[6:7], s[60:61]
	s_and_b64 s[56:57], s[16:17], s[56:57]
	s_branch .Lnaa_end
.Lnaa_loc:
	v_readlane_b32 s6, v254, 55
	v_readlane_b32 s7, v254, 56
	s_and_b64 s[62:63], s[4:5], s[6:7]
	s_waitcnt lgkmcnt(0)
	v_mov_b32_e32 v207, 0xf149f2ca
	s_mov_b64 vcc, s[62:63]
	v_add_f32_e32 v133, v92, v208
	v_cndmask_b32_e32 v92, v207, v133, vcc
	v_readlane_b32 s6, v254, 57
	v_readlane_b32 s7, v254, 58
	s_and_b64 s[62:63], s[4:5], s[6:7]
	s_mov_b64 vcc, s[62:63]
	v_add_f32_e32 v133, v93, v210
	v_cndmask_b32_e32 v93, v207, v133, vcc
	v_readlane_b32 s6, v254, 59
	v_readlane_b32 s7, v254, 60
	s_and_b64 s[62:63], s[4:5], s[6:7]
	s_mov_b64 vcc, s[62:63]
	v_add_f32_e32 v133, v94, v209
	v_cndmask_b32_e32 v94, v207, v133, vcc
	v_readlane_b32 s6, v254, 61
	v_readlane_b32 s7, v254, 62
	s_and_b64 s[6:7], s[4:5], s[6:7]
	s_mov_b64 vcc, s[6:7]
	v_add_f32_e32 v133, v95, v211
	v_cndmask_b32_e32 v95, v207, v133, vcc
	v_readlane_b32 s4, v254, 63
	v_readlane_b32 s5, v255, 0
	s_and_b64 s[62:63], s[58:59], s[4:5]
	s_and_b64 s[4:5], s[62:63], s[60:61]
	s_and_b64 s[4:5], s[4:5], s[56:57]
	v_readlane_b32 s6, v255, 1
	v_readlane_b32 s7, v255, 2
	v_readlane_b32 s16, v255, 3
	s_and_b64 s[6:7], s[4:5], s[6:7]
	v_readlane_b32 s17, v255, 4
	s_and_b64 vcc, s[6:7], s[16:17]
	v_add_f32_e32 v133, v88, v212
	v_cndmask_b32_e32 v88, v207, v133, vcc
	v_readlane_b32 s6, v255, 5
	v_readlane_b32 s7, v255, 6
	s_and_b64 s[6:7], s[4:5], s[6:7]
	s_and_b64 vcc, s[6:7], s[18:19]
	v_add_f32_e32 v133, v89, v214
	v_cndmask_b32_e32 v89, v207, v133, vcc
	s_and_b64 s[6:7], s[4:5], s[20:21]
	s_and_b64 vcc, s[6:7], s[22:23]
	v_add_f32_e32 v133, v90, v213
	v_cndmask_b32_e32 v90, v207, v133, vcc
	s_and_b64 s[4:5], s[4:5], s[24:25]
	s_and_b64 s[6:7], s[4:5], s[26:27]
	s_mov_b64 vcc, s[6:7]
	v_add_f32_e32 v133, v91, v215
	v_cndmask_b32_e32 v91, v207, v133, vcc
	s_and_b64 s[4:5], s[58:59], s[2:3]
	s_and_b64 s[6:7], s[4:5], s[60:61]
	s_and_b64 s[6:7], s[6:7], s[56:57]
	s_and_b64 vcc, s[6:7], s[28:29]
	s_and_b64 s[16:17], vcc, s[30:31]
	s_mov_b64 vcc, s[16:17]
	v_add_f32_e32 v133, v68, v216
	v_cndmask_b32_e32 v68, v207, v133, vcc
	s_and_b64 s[16:17], s[6:7], s[34:35]
	s_and_b64 s[16:17], s[16:17], s[36:37]
	s_mov_b64 vcc, s[16:17]
	v_add_f32_e32 v133, v69, v218
	v_cndmask_b32_e32 v69, v207, v133, vcc
	s_and_b64 s[16:17], s[6:7], s[38:39]
	s_and_b64 s[16:17], s[16:17], s[8:9]
	s_mov_b64 vcc, s[16:17]
	v_add_f32_e32 v133, v70, v217
	v_cndmask_b32_e32 v70, v207, v133, vcc
	s_and_b64 s[6:7], s[6:7], s[10:11]
	s_and_b64 s[16:17], s[6:7], s[0:1]
	s_mov_b64 vcc, s[16:17]
	v_add_f32_e32 v133, v71, v219
	v_cndmask_b32_e32 v71, v207, v133, vcc
	s_and_b64 s[6:7], s[58:59], s[68:69]
	s_and_b64 s[16:17], s[6:7], s[60:61]
	s_and_b64 s[56:57], s[16:17], s[56:57]
	s_and_b64 s[16:17], s[56:57], s[12:13]
	s_mov_b64 vcc, s[16:17]
	v_add_f32_e32 v133, v64, v220
	v_cndmask_b32_e32 v64, v207, v133, vcc
	s_and_b64 s[16:17], s[56:57], s[48:49]
	s_mov_b64 vcc, s[16:17]
	v_add_f32_e32 v133, v65, v222
	v_cndmask_b32_e32 v65, v207, v133, vcc
	s_and_b64 s[16:17], s[56:57], s[50:51]
	s_mov_b64 vcc, s[16:17]
	v_add_f32_e32 v133, v66, v221
	v_cndmask_b32_e32 v66, v207, v133, vcc
	s_and_b64 s[16:17], s[56:57], s[52:53]
	s_mov_b64 vcc, s[16:17]
	v_add_f32_e32 v133, v67, v223
	v_cndmask_b32_e32 v67, v207, v133, vcc
.Lnaa_end:
	s_mov_b32 s16, 0xf149f2ca
	v_max3_f32 v133, v92, s16, v93
	v_max3_f32 v133, v133, v94, v95
	v_max3_f32 v133, v133, v88, v89
	v_max3_f32 v133, v133, v90, v91
	v_max3_f32 v133, v133, v68, v69
	v_max3_f32 v133, v133, v70, v71
	v_max3_f32 v133, v133, v64, v65
	v_max3_f32 v133, v133, v66, v67
	ds_bpermute_b32 v134, v106, v133
	v_cmp_ge_i32_e64 s[58:59], v127, v119
	v_cmp_lt_i32_e64 s[56:57], v127, v120
	s_and_b64 s[16:17], s[96:97], s[58:59]
	s_waitcnt lgkmcnt(0)
	v_max_f32_e32 v134, v134, v134
	v_max_f32_e32 v133, v133, v134
	ds_bpermute_b32 v134, v105, v133
	s_and_b64 s[60:61], s[16:17], s[56:57]
	s_and_b64 vcc, exec, s[54:55]
	s_cbranch_vccz .Lnab_loc
	s_and_b64 s[16:17], s[62:63], s[58:59]
	s_and_b64 s[60:61], s[16:17], s[56:57]
	s_and_b64 s[4:5], s[4:5], s[58:59]
	s_and_b64 s[4:5], s[4:5], s[56:57]
	s_and_b64 s[4:5], s[6:7], s[58:59]
	s_and_b64 s[6:7], s[4:5], s[56:57]
	s_mov_b64 s[4:5], -1
	s_branch .Lnab_end
.Lnab_loc:
	v_readlane_b32 s16, v254, 55
	v_readlane_b32 s17, v254, 56
	s_and_b64 s[16:17], s[60:61], s[16:17]
	s_waitcnt lgkmcnt(0)
	v_mov_b32_e32 v207, 0xf149f2ca
	s_mov_b64 vcc, s[16:17]
	v_add_f32_e32 v127, v84, v224
	v_cndmask_b32_e32 v84, v207, v127, vcc
	v_readlane_b32 s16, v254, 57
	v_readlane_b32 s17, v254, 58
	s_and_b64 s[16:17], s[60:61], s[16:17]
	s_mov_b64 vcc, s[16:17]
	v_add_f32_e32 v127, v85, v228
	v_cndmask_b32_e32 v85, v207, v127, vcc
	v_readlane_b32 s16, v254, 59
	v_readlane_b32 s17, v254, 60
	s_and_b64 s[16:17], s[60:61], s[16:17]
	s_mov_b64 vcc, s[16:17]
	v_add_f32_e32 v127, v86, v225
	v_cndmask_b32_e32 v86, v207, v127, vcc
	v_readlane_b32 s16, v254, 61
	v_readlane_b32 s17, v254, 62
	s_and_b64 s[16:17], s[60:61], s[16:17]
	s_mov_b64 vcc, s[16:17]
	v_add_f32_e32 v127, v87, v229
	v_cndmask_b32_e32 v87, v207, v127, vcc
	s_and_b64 s[16:17], s[62:63], s[58:59]
	s_and_b64 s[60:61], s[16:17], s[56:57]
	v_readlane_b32 s16, v255, 1
	v_readlane_b32 s17, v255, 2
	v_readlane_b32 s62, v255, 3
	s_and_b64 s[16:17], s[60:61], s[16:17]
	v_readlane_b32 s63, v255, 4
	s_and_b64 s[16:17], s[16:17], s[62:63]
	s_mov_b64 vcc, s[16:17]
	v_add_f32_e32 v127, v80, v226
	v_cndmask_b32_e32 v80, v207, v127, vcc
	v_readlane_b32 s16, v255, 5
	v_readlane_b32 s17, v255, 6
	s_and_b64 s[16:17], s[60:61], s[16:17]
	s_and_b64 s[16:17], s[16:17], s[18:19]
	s_mov_b64 vcc, s[16:17]
	v_add_f32_e32 v127, v81, v230
	v_cndmask_b32_e32 v81, v207, v127, vcc
	s_and_b64 s[16:17], s[60:61], s[20:21]
	s_and_b64 s[16:17], s[16:17], s[22:23]
	s_mov_b64 vcc, s[16:17]
	v_add_f32_e32 v127, v82, v227
	v_cndmask_b32_e32 v82, v207, v127, vcc
	s_and_b64 s[16:17], s[60:61], s[24:25]
	s_and_b64 s[16:17], s[16:17], s[26:27]
	s_mov_b64 vcc, s[16:17]
	v_add_f32_e32 v127, v83, v231
	v_cndmask_b32_e32 v83, v207, v127, vcc
	s_and_b64 s[4:5], s[4:5], s[58:59]
	s_and_b64 s[4:5], s[4:5], s[56:57]
	s_and_b64 s[16:17], s[4:5], s[28:29]
	s_and_b64 s[16:17], s[16:17], s[30:31]
	s_mov_b64 vcc, s[16:17]
	v_add_f32_e32 v127, v76, v210
	v_cndmask_b32_e32 v76, v207, v127, vcc
	s_and_b64 s[16:17], s[4:5], s[34:35]
	s_and_b64 s[16:17], s[16:17], s[36:37]
	s_mov_b64 vcc, s[16:17]
	v_add_f32_e32 v127, v77, v209
	v_cndmask_b32_e32 v77, v207, v127, vcc
	s_and_b64 s[16:17], s[4:5], s[38:39]
	s_and_b64 s[16:17], s[16:17], s[8:9]
	s_mov_b64 vcc, s[16:17]
	v_add_f32_e32 v127, v78, v211
	v_cndmask_b32_e32 v78, v207, v127, vcc
	s_and_b64 s[4:5], s[4:5], s[10:11]
	s_and_b64 s[16:17], s[4:5], s[0:1]
	s_mov_b64 vcc, s[16:17]
	v_add_f32_e32 v127, v79, v232
	v_cndmask_b32_e32 v79, v207, v127, vcc
	s_and_b64 s[4:5], s[6:7], s[58:59]
	s_and_b64 s[6:7], s[4:5], s[56:57]
	s_and_b64 s[16:17], s[6:7], s[12:13]
	s_mov_b64 vcc, s[16:17]
	v_add_f32_e32 v127, v72, v214
	v_cndmask_b32_e32 v72, v207, v127, vcc
	s_and_b64 s[16:17], s[6:7], s[48:49]
	s_mov_b64 vcc, s[16:17]
	v_add_f32_e32 v127, v73, v213
	v_cndmask_b32_e32 v73, v207, v127, vcc
	s_and_b64 s[16:17], s[6:7], s[50:51]
	s_mov_b64 vcc, s[16:17]
	v_add_f32_e32 v127, v74, v215
	v_cndmask_b32_e32 v74, v207, v127, vcc
	s_mov_b64 s[4:5], -1
	s_and_b64 s[6:7], s[6:7], s[52:53]
	s_mov_b64 vcc, s[6:7]
	v_add_f32_e32 v127, v75, v233
	v_cndmask_b32_e32 v75, v207, v127, vcc
	s_mov_b64 s[4:5], s[64:65]
